# attention loop: first two QK MFMAs of each step hoisted to the step head (MFMA-first after the barrier), on top of VALU diet
# baseline (speedup 1.0000x reference)
.LBB0_304:
	s_mov_b32 s37, s28
	s_mov_b32 s14, s27
	v_mfma_f32_32x32x16_bf16 v[128:143], v[204:207], v[168:171], 0
	v_mfma_f32_32x32x16_bf16 v[112:127], v[200:203], v[168:171], 0
	v_lshl_add_u32 v65, s15, 1, v239
	ds_read_b64_tr_b16 v[72:73], v65 offset:24576
	ds_read_b64_tr_b16 v[74:75], v65 offset:25088
	v_add_f32_e32 v68, v96, v97
	v_add_f32_e32 v68, v98, v68
	v_add_f32_e32 v68, v99, v68
	v_add_f32_e32 v68, v100, v68
	v_add_f32_e32 v68, v101, v68
	v_cvt_pk_bf16_f32 v172, v96, v97
	v_cvt_pk_bf16_f32 v173, v98, v99
	ds_read_b64_tr_b16 v[76:77], v65 offset:28672
	ds_read_b64_tr_b16 v[78:79], v65 offset:29184
	v_add_f32_e32 v68, v102, v68
	v_add_f32_e32 v68, v103, v68
	v_add_f32_e32 v68, v104, v68
	v_add_f32_e32 v68, v105, v68
	v_cvt_pk_bf16_f32 v174, v100, v101
	v_cvt_pk_bf16_f32 v175, v102, v103
	ds_read_b64_tr_b16 v[96:97], v65 offset:32768
	ds_read_b64_tr_b16 v[98:99], v65 offset:33280
	v_add_f32_e32 v68, v106, v68
	v_add_f32_e32 v68, v107, v68
	v_add_f32_e32 v68, v108, v68
	v_add_f32_e32 v68, v109, v68
	v_cvt_pk_bf16_f32 v164, v104, v105
	v_cvt_pk_bf16_f32 v165, v106, v107
	s_waitcnt lgkmcnt(11)
	v_mfma_f32_32x32x16_bf16 v[128:143], v[196:199], v[160:163], v[128:143]
	ds_read_b64_tr_b16 v[100:101], v65 offset:36864
	ds_read_b64_tr_b16 v[102:103], v65 offset:37376
	v_add_f32_e32 v68, v110, v68
	v_add_f32_e32 v68, v111, v68
	v_add_f32_e32 v68, v80, v68
	v_add_f32_e32 v68, v81, v68
	v_cvt_pk_bf16_f32 v166, v108, v109
	v_cvt_pk_bf16_f32 v167, v110, v111
	s_waitcnt lgkmcnt(12)
	v_mfma_f32_32x32x16_bf16 v[112:127], v[192:195], v[160:163], v[112:127]
	ds_read_b64_tr_b16 v[104:105], v65 offset:25600
	ds_read_b64_tr_b16 v[106:107], v65 offset:26112
	v_add_f32_e32 v68, v82, v68
	v_add_f32_e32 v68, v83, v68
	v_add_f32_e32 v68, v84, v68
	v_add_f32_e32 v68, v85, v68
	v_cvt_pk_bf16_f32 v156, v80, v81
	v_cvt_pk_bf16_f32 v157, v82, v83
	s_waitcnt lgkmcnt(13)
	v_mfma_f32_32x32x16_bf16 v[128:143], v[188:191], v[152:155], v[128:143]
	ds_read_b64_tr_b16 v[80:81], v65 offset:29696
	ds_read_b64_tr_b16 v[82:83], v65 offset:30208
	v_add_f32_e32 v68, v86, v68
	v_add_f32_e32 v68, v87, v68
	v_add_f32_e32 v68, v88, v68
	v_add_f32_e32 v68, v89, v68
	v_cvt_pk_bf16_f32 v158, v84, v85
	v_cvt_pk_bf16_f32 v159, v86, v87
	s_waitcnt lgkmcnt(14)
	v_mfma_f32_32x32x16_bf16 v[112:127], v[184:187], v[152:155], v[112:127]
	ds_read_b64_tr_b16 v[84:85], v65 offset:33792
	ds_read_b64_tr_b16 v[86:87], v65 offset:34304
	v_add_f32_e32 v68, v90, v68
	v_add_f32_e32 v68, v91, v68
	v_add_f32_e32 v68, v92, v68
	v_add_f32_e32 v68, v93, v68
	v_cvt_pk_bf16_f32 v148, v88, v89
	v_cvt_pk_bf16_f32 v149, v90, v91
	s_waitcnt lgkmcnt(14)
	v_mfma_f32_32x32x16_bf16 v[128:143], v[180:183], v[144:147], v[128:143]
	ds_read_b64_tr_b16 v[88:89], v65 offset:37888
	ds_read_b64_tr_b16 v[90:91], v65 offset:38400
	v_add_f32_e32 v68, v94, v68
	v_add_f32_e32 v68, v95, v68
	v_cvt_pk_bf16_f32 v150, v92, v93
	v_cvt_pk_bf16_f32 v151, v94, v95
	v_mfma_f32_32x32x16_bf16 v[112:127], v[176:179], v[144:147], v[112:127]
	v_add_f32_e32 v64, v64, v68
	s_waitcnt lgkmcnt(14)
	v_mfma_f32_32x32x16_bf16 v[48:63], v[172:175], v[72:75], v[48:63]
	v_exp_f32_e32 v128, v128
	v_exp_f32_e32 v129, v129
	ds_read_b64_tr_b16 v[72:73], v65 offset:26624
	ds_read_b64_tr_b16 v[74:75], v65 offset:27136
	s_waitcnt lgkmcnt(14)
	v_mfma_f32_32x32x16_bf16 v[32:47], v[172:175], v[76:79], v[32:47]
	v_exp_f32_e32 v130, v130
	v_exp_f32_e32 v131, v131
	ds_read_b64_tr_b16 v[76:77], v65 offset:30720
	ds_read_b64_tr_b16 v[78:79], v65 offset:31232
	s_add_i32 s15, s27, s20
	s_mov_b32 m0, s15
	s_nop 0
	global_load_lds_dwordx4 v250, s[98:99]
	s_add_u32 s98, s98, 0x60000
	s_addc_u32 s99, s99, 0
	s_waitcnt lgkmcnt(14)
	v_mfma_f32_32x32x16_bf16 v[16:31], v[172:175], v[96:99], v[16:31]
	v_exp_f32_e32 v132, v132
	v_exp_f32_e32 v133, v133
	ds_read_b64_tr_b16 v[92:93], v65 offset:34816
	ds_read_b64_tr_b16 v[94:95], v65 offset:35328
	s_waitcnt lgkmcnt(14)
	v_mfma_f32_32x32x16_bf16 v[0:15], v[172:175], v[100:103], v[0:15]
	v_exp_f32_e32 v134, v134
	v_exp_f32_e32 v135, v135
	ds_read_b64_tr_b16 v[96:97], v65 offset:38912
	ds_read_b64_tr_b16 v[98:99], v65 offset:39424
	s_waitcnt lgkmcnt(14)
	v_mfma_f32_32x32x16_bf16 v[48:63], v[164:167], v[104:107], v[48:63]
	v_exp_f32_e32 v136, v136
	v_exp_f32_e32 v137, v137
	ds_read_b64_tr_b16 v[100:101], v65 offset:27648
	ds_read_b64_tr_b16 v[102:103], v65 offset:28160
	s_lshl_b32 s15, s28, 1
	s_add_i32 s15, s15, s21
	s_mov_b32 m0, s15
	s_nop 0
	global_load_lds_dwordx4 v251, s[100:101]
	s_waitcnt lgkmcnt(14)
	v_mfma_f32_32x32x16_bf16 v[32:47], v[164:167], v[80:83], v[32:47]
	v_exp_f32_e32 v138, v138
	v_exp_f32_e32 v139, v139
	ds_read_b64_tr_b16 v[80:81], v65 offset:31744
	ds_read_b64_tr_b16 v[82:83], v65 offset:32256
	s_waitcnt lgkmcnt(14)
	v_mfma_f32_32x32x16_bf16 v[16:31], v[164:167], v[84:87], v[16:31]
	v_exp_f32_e32 v140, v140
	v_exp_f32_e32 v141, v141
	ds_read_b64_tr_b16 v[84:85], v65 offset:35840
	ds_read_b64_tr_b16 v[86:87], v65 offset:36352
	s_waitcnt lgkmcnt(14)
	v_mfma_f32_32x32x16_bf16 v[0:15], v[164:167], v[88:91], v[0:15]
	v_exp_f32_e32 v142, v142
	v_exp_f32_e32 v143, v143
	ds_read_b64_tr_b16 v[88:89], v65 offset:39936
	ds_read_b64_tr_b16 v[90:91], v65 offset:40448
	s_lshl_b32 s15, s28, 1
	s_add_i32 s15, s15, s21
	s_addk_i32 s15, 0x1f80
	s_mov_b32 m0, s15
	s_nop 0
	global_load_lds_dwordx4 v251, s[100:101] offset:128
	s_add_u32 s100, s100, 0x60000
	s_addc_u32 s101, s101, 0
	s_waitcnt lgkmcnt(14)
	v_mfma_f32_32x32x16_bf16 v[48:63], v[156:159], v[72:75], v[48:63]
	v_exp_f32_e32 v112, v112
	v_exp_f32_e32 v113, v113
	s_waitcnt lgkmcnt(12)
	v_mfma_f32_32x32x16_bf16 v[32:47], v[156:159], v[76:79], v[32:47]
	v_exp_f32_e32 v114, v114
	v_exp_f32_e32 v115, v115
	v_add_u32_e32 v65, s37, v241
	ds_read_b128 v[72:75], v65
	ds_read_b128 v[76:79], v65 offset:512
	s_waitcnt lgkmcnt(12)
	v_mfma_f32_32x32x16_bf16 v[16:31], v[156:159], v[92:95], v[16:31]
	v_exp_f32_e32 v116, v116
	v_exp_f32_e32 v117, v117
	ds_read_b128 v[176:179], v65 offset:2048
	ds_read_b128 v[180:183], v65 offset:2560
	s_waitcnt lgkmcnt(12)
	v_mfma_f32_32x32x16_bf16 v[0:15], v[156:159], v[96:99], v[0:15]
	v_exp_f32_e32 v118, v118
	v_exp_f32_e32 v119, v119
	ds_read_b128 v[184:187], v65 offset:4096
	ds_read_b128 v[188:191], v65 offset:4608
	s_waitcnt lgkmcnt(12)
	v_mfma_f32_32x32x16_bf16 v[48:63], v[148:151], v[100:103], v[48:63]
	v_exp_f32_e32 v120, v120
	v_exp_f32_e32 v121, v121
	ds_read_b128 v[192:195], v65 offset:6144
	ds_read_b128 v[196:199], v65 offset:6656
	s_waitcnt lgkmcnt(12)
	v_mfma_f32_32x32x16_bf16 v[32:47], v[148:151], v[80:83], v[32:47]
	v_exp_f32_e32 v122, v122
	v_exp_f32_e32 v123, v123
	s_waitcnt lgkmcnt(10)
	v_mfma_f32_32x32x16_bf16 v[16:31], v[148:151], v[84:87], v[16:31]
	v_exp_f32_e32 v124, v124
	v_exp_f32_e32 v125, v125
	s_waitcnt lgkmcnt(8)
	v_mfma_f32_32x32x16_bf16 v[0:15], v[148:151], v[88:91], v[0:15]
	v_exp_f32_e32 v126, v126
	v_exp_f32_e32 v127, v127
	s_waitcnt vmcnt(3) lgkmcnt(0)
	s_barrier
	v_mfma_f32_32x32x16_bf16 v[96:111], v[72:75], v[168:171], 0
	v_mfma_f32_32x32x16_bf16 v[80:95], v[76:79], v[168:171], 0
	s_add_i32 s15, s28, 0x2000
	s_cmpk_lg_i32 s28, 0x4000
	s_cselect_b32 s27, s15, 0
	v_lshl_add_u32 v65, s14, 1, v239
	ds_read_b64_tr_b16 v[200:201], v65 offset:24576
	ds_read_b64_tr_b16 v[202:203], v65 offset:25088
	v_add_f32_e32 v243, v128, v129
	v_add_f32_e32 v243, v130, v243
	v_add_f32_e32 v243, v131, v243
	v_add_f32_e32 v243, v132, v243
	v_add_f32_e32 v243, v133, v243
	v_cvt_pk_bf16_f32 v172, v128, v129
	v_cvt_pk_bf16_f32 v173, v130, v131
	ds_read_b64_tr_b16 v[72:73], v65 offset:28672
	ds_read_b64_tr_b16 v[74:75], v65 offset:29184
	v_add_f32_e32 v243, v134, v243
	v_add_f32_e32 v243, v135, v243
	v_add_f32_e32 v243, v136, v243
	v_add_f32_e32 v128, v137, v243
	v_cvt_pk_bf16_f32 v174, v132, v133
	v_cvt_pk_bf16_f32 v175, v134, v135
	ds_read_b64_tr_b16 v[76:77], v65 offset:32768
	ds_read_b64_tr_b16 v[78:79], v65 offset:33280
	s_waitcnt lgkmcnt(11)
	v_mfma_f32_32x32x16_bf16 v[96:111], v[176:179], v[160:163], v[96:111]
	v_add_f32_e32 v128, v138, v128
	v_add_f32_e32 v128, v139, v128
	v_add_f32_e32 v128, v140, v128
	v_add_f32_e32 v132, v141, v128
	v_cvt_pk_bf16_f32 v164, v136, v137
	v_cvt_pk_bf16_f32 v165, v138, v139
	ds_read_b64_tr_b16 v[128:129], v65 offset:36864
	ds_read_b64_tr_b16 v[130:131], v65 offset:37376
	s_waitcnt lgkmcnt(12)
	v_mfma_f32_32x32x16_bf16 v[80:95], v[180:183], v[160:163], v[80:95]
	v_add_f32_e32 v132, v142, v132
	v_add_f32_e32 v132, v143, v132
	v_add_f32_e32 v132, v112, v132
	v_add_f32_e32 v136, v113, v132
	v_cvt_pk_bf16_f32 v166, v140, v141
	v_cvt_pk_bf16_f32 v167, v142, v143
	ds_read_b64_tr_b16 v[132:133], v65 offset:25600
	ds_read_b64_tr_b16 v[134:135], v65 offset:26112
	s_waitcnt lgkmcnt(13)
	v_mfma_f32_32x32x16_bf16 v[96:111], v[184:187], v[152:155], v[96:111]
	v_add_f32_e32 v136, v114, v136
	v_add_f32_e32 v136, v115, v136
	v_add_f32_e32 v136, v116, v136
	v_add_f32_e32 v136, v117, v136
	v_cvt_pk_bf16_f32 v156, v112, v113
	v_cvt_pk_bf16_f32 v157, v114, v115
	ds_read_b64_tr_b16 v[112:113], v65 offset:29696
	ds_read_b64_tr_b16 v[114:115], v65 offset:30208
	s_waitcnt lgkmcnt(14)
	v_mfma_f32_32x32x16_bf16 v[80:95], v[188:191], v[152:155], v[80:95]
	v_add_f32_e32 v136, v118, v136
	v_add_f32_e32 v136, v119, v136
	v_add_f32_e32 v136, v120, v136
	v_add_f32_e32 v136, v121, v136
	v_cvt_pk_bf16_f32 v158, v116, v117
	v_cvt_pk_bf16_f32 v159, v118, v119
	ds_read_b64_tr_b16 v[116:117], v65 offset:33792
	ds_read_b64_tr_b16 v[118:119], v65 offset:34304
	s_waitcnt lgkmcnt(14)
	v_mfma_f32_32x32x16_bf16 v[96:111], v[192:195], v[144:147], v[96:111]
	v_add_f32_e32 v136, v122, v136
	v_add_f32_e32 v136, v123, v136
	v_add_f32_e32 v136, v124, v136
	v_add_f32_e32 v136, v125, v136
	v_cvt_pk_bf16_f32 v148, v120, v121
	v_cvt_pk_bf16_f32 v149, v122, v123
	ds_read_b64_tr_b16 v[120:121], v65 offset:37888
	ds_read_b64_tr_b16 v[122:123], v65 offset:38400
	v_mfma_f32_32x32x16_bf16 v[80:95], v[196:199], v[144:147], v[80:95]
	v_add_f32_e32 v136, v126, v136
	v_add_f32_e32 v136, v127, v136
	v_cvt_pk_bf16_f32 v150, v124, v125
	v_cvt_pk_bf16_f32 v151, v126, v127
	v_add_f32_e32 v64, v64, v136
	s_add_i32 s35, s35, 2
	s_waitcnt lgkmcnt(14)
	v_mfma_f32_32x32x16_bf16 v[48:63], v[172:175], v[200:203], v[48:63]
	v_exp_f32_e32 v96, v96
	v_exp_f32_e32 v97, v97
	ds_read_b64_tr_b16 v[68:69], v65 offset:26624
	ds_read_b64_tr_b16 v[70:71], v65 offset:27136
	s_waitcnt lgkmcnt(14)
	v_mfma_f32_32x32x16_bf16 v[32:47], v[172:175], v[72:75], v[32:47]
	v_exp_f32_e32 v98, v98
	v_exp_f32_e32 v99, v99
	ds_read_b64_tr_b16 v[72:73], v65 offset:30720
	ds_read_b64_tr_b16 v[74:75], v65 offset:31232
	s_add_i32 s24, s28, s20
	s_mov_b32 m0, s24
	s_nop 0
	global_load_lds_dwordx4 v250, s[98:99]
	s_add_u32 s98, s98, 0x60000
	s_addc_u32 s99, s99, 0
	s_waitcnt lgkmcnt(14)
; #define WAIT_BAR(N) asm volatile("s_waitcnt vmcnt(" #N ") lgkmcnt(0)\n\ts_barrier":::"memory")
;   #define ROT() do{sl_prev=sl_cur;sl_cur=sl_next;sl_next=(sl_next==(NSLOT-1)*SLOTB)?0:sl_next+SLOTB;}while(0)
; template<int DUMMY> __device__ __forceinline__ void attn_pass2(const bf16*Qh,const bf16*__restrict__ Kh,const bf16*__restrict__ Vh,const int q0,char*shm,f32x16 (&o)[4]){
;     ...
;   int t=1;
;     ...
;   for(;t+5<NT;t+=2){
;     STEP(pB0,pB1,pA0,pA1,t,true,true,true);     WAIT_BAR(3); ROT();
;     STEP(pA0,pA1,pB0,pB1,t+1,true,true,true);   WAIT_BAR(3); ROT();
	v_mfma_f32_32x32x16_bf16 v[16:31], v[172:175], v[76:79], v[16:31]
	v_exp_f32_e32 v100, v100
	v_exp_f32_e32 v101, v101
	ds_read_b64_tr_b16 v[76:77], v65 offset:34816
	ds_read_b64_tr_b16 v[78:79], v65 offset:35328
	s_waitcnt lgkmcnt(14)
	v_mfma_f32_32x32x16_bf16 v[0:15], v[172:175], v[128:131], v[0:15]
	v_exp_f32_e32 v102, v102
	v_exp_f32_e32 v103, v103
	ds_read_b64_tr_b16 v[124:125], v65 offset:38912
	ds_read_b64_tr_b16 v[126:127], v65 offset:39424
	s_waitcnt lgkmcnt(14)
	v_mfma_f32_32x32x16_bf16 v[48:63], v[164:167], v[132:135], v[48:63]
	v_exp_f32_e32 v104, v104
	v_exp_f32_e32 v105, v105
	ds_read_b64_tr_b16 v[128:129], v65 offset:27648
	ds_read_b64_tr_b16 v[130:131], v65 offset:28160
	s_lshl_b32 s24, s27, 1
	s_add_i32 s24, s24, s21
	s_mov_b32 m0, s24
	s_nop 0
	global_load_lds_dwordx4 v251, s[100:101]
	s_waitcnt lgkmcnt(14)
	v_mfma_f32_32x32x16_bf16 v[32:47], v[164:167], v[112:115], v[32:47]
	v_exp_f32_e32 v106, v106
	v_exp_f32_e32 v107, v107
	ds_read_b64_tr_b16 v[112:113], v65 offset:31744
	ds_read_b64_tr_b16 v[114:115], v65 offset:32256
	s_waitcnt lgkmcnt(14)
	v_mfma_f32_32x32x16_bf16 v[16:31], v[164:167], v[116:119], v[16:31]
	v_exp_f32_e32 v108, v108
	v_exp_f32_e32 v109, v109
	ds_read_b64_tr_b16 v[116:117], v65 offset:35840
	ds_read_b64_tr_b16 v[118:119], v65 offset:36352
	s_waitcnt lgkmcnt(14)
	v_mfma_f32_32x32x16_bf16 v[0:15], v[164:167], v[120:123], v[0:15]
	v_exp_f32_e32 v110, v110
	v_exp_f32_e32 v111, v111
	ds_read_b64_tr_b16 v[120:121], v65 offset:39936
	ds_read_b64_tr_b16 v[122:123], v65 offset:40448
	s_lshl_b32 s24, s27, 1
	s_add_i32 s24, s24, s21
	s_addk_i32 s24, 0x1f80
	s_mov_b32 m0, s24
	s_nop 0
	global_load_lds_dwordx4 v251, s[100:101] offset:128
	s_add_u32 s100, s100, 0x60000
	s_addc_u32 s101, s101, 0
	s_waitcnt lgkmcnt(14)
	v_mfma_f32_32x32x16_bf16 v[48:63], v[156:159], v[68:71], v[48:63]
	v_exp_f32_e32 v80, v80
	v_exp_f32_e32 v81, v81
	s_waitcnt lgkmcnt(12)
	v_mfma_f32_32x32x16_bf16 v[32:47], v[156:159], v[72:75], v[32:47]
	v_exp_f32_e32 v82, v82
	v_exp_f32_e32 v83, v83
	v_add_u32_e32 v65, s27, v241
	ds_read_b128 v[204:207], v65
	ds_read_b128 v[200:203], v65 offset:512
	s_waitcnt lgkmcnt(12)
	v_mfma_f32_32x32x16_bf16 v[16:31], v[156:159], v[76:79], v[16:31]
	v_exp_f32_e32 v84, v84
	v_exp_f32_e32 v85, v85
	ds_read_b128 v[196:199], v65 offset:2048
	ds_read_b128 v[192:195], v65 offset:2560
	s_waitcnt lgkmcnt(12)
	v_mfma_f32_32x32x16_bf16 v[0:15], v[156:159], v[124:127], v[0:15]
	v_exp_f32_e32 v86, v86
	v_exp_f32_e32 v87, v87
	ds_read_b128 v[188:191], v65 offset:4096
	ds_read_b128 v[184:187], v65 offset:4608
	s_waitcnt lgkmcnt(12)
	v_mfma_f32_32x32x16_bf16 v[48:63], v[148:151], v[128:131], v[48:63]
	v_exp_f32_e32 v88, v88
	v_exp_f32_e32 v89, v89
	ds_read_b128 v[180:183], v65 offset:6144
	ds_read_b128 v[176:179], v65 offset:6656
	s_waitcnt lgkmcnt(12)
	v_mfma_f32_32x32x16_bf16 v[32:47], v[148:151], v[112:115], v[32:47]
	v_exp_f32_e32 v90, v90
	v_exp_f32_e32 v91, v91
	s_waitcnt lgkmcnt(10)
	v_mfma_f32_32x32x16_bf16 v[16:31], v[148:151], v[116:119], v[16:31]
	v_exp_f32_e32 v92, v92
	v_exp_f32_e32 v93, v93
	s_waitcnt lgkmcnt(8)
	v_mfma_f32_32x32x16_bf16 v[0:15], v[148:151], v[120:123], v[0:15]
	v_exp_f32_e32 v94, v94
	v_exp_f32_e32 v95, v95
	s_add_i32 s14, s27, 0x2000
	s_cmpk_lg_i32 s27, 0x4000
	s_waitcnt vmcnt(3) lgkmcnt(0)
	s_barrier
	s_cselect_b32 s28, s14, 0
	s_add_u32 s56, s56, 0xc0000
	s_addc_u32 s57, s57, 0
	s_cmp_ge_i32 s35, s11
	s_mov_b32 s15, s37
	s_cbranch_scc0 .LBB0_304
	s_ashr_i32 s11, s10, 31
	s_add_i32 s14, s35, 1
	s_cmp_lt_i32 s14, s25
	s_cbranch_scc1 .LBB0_315
